# compress item: the 4 serialized W2 loads + LDS reads of the second small GEMM issued together
# baseline (speedup 1.0000x reference)
; #define TIDX opaque_tid()
; #define AIN(i) ((const float*)(__attribute__((address_space(1))) const float*)karg_u64(8 * (i)))
; __device__ __forceinline__ f32x4 mfma16(bf16x8 a, bf16x8 b, f32x4 c) { return __builtin_amdgcn_mfma_f32_16x16x32_bf16(a, b, c, 0, 0, 0); }
; #define WSP(T, off) ((T*)(__attribute__((address_space(1))) T*)(launder_ws(AWS, (off))))
; __device__ __forceinline__ void compress_item(const Args& a, int l, int it, unsigned char* lds, unsigned* cmp_done) {
;     const int which = it >> 6, bg = (it >> 4) & 3, rg = it & 15;
;     const int tid = TIDX, w = tid >> 6, lane = tid & 63, fr = lane & 15, fq = lane >> 4;
;     const float* X = WSP(const float, which ? WS_VCR : WS_KCR) + (size_t)bg * SEQ * 128;
;     const float* pe = sel_ptr(which != 0, AIN(9), AIN(8)) + (size_t)l * 32 * 128;
;     const bf16_t* W1t = WSP(const bf16_t, which ? WS_CV1 : WS_CK1);
;     const bf16_t* W2t = WSP(const bf16_t, which ? WS_CV2 : WS_CK2);
;     bf16_t* Hs = (bf16_t*)lds;
;     float* Part = (float*)(lds + 8192);
;     const int nc = rg * 16 + fr, ncl = nc < 255 ? nc : 254;
;     const float* arow = X + (size_t)ncl * 16 * 128 + w * 512 + fq * 8;
;     const bf16_t* brow = W1t + (size_t)fr * 4096 + w * 512 + fq * 8;
;     const float* per = pe + w * 512 + fq * 8;
;     f32x4 acc[8];
; #pragma unroll
;     for (int nt = 0; nt < 8; ++nt) acc[nt] = zero4();
;     __syncthreads();
; #pragma unroll 2
;     for (int kk = 0; kk < 16; ++kk) {
;         const f32x4 x0 = *(const f32x4*)(arow + kk * 32), x1 = *(const f32x4*)(arow + kk * 32 + 4);
;         const f32x4 p0 = *(const f32x4*)(per + kk * 32), p1 = *(const f32x4*)(per + kk * 32 + 4);
;         bf16x8 bfr[8];
; #pragma unroll
;         for (int nt = 0; nt < 8; ++nt) bfr[nt] = *(const bf16x8*)(brow + (size_t)nt * 16 * 4096 + kk * 32);
;         const bf16x8 av = pack8(x0 + p0, x1 + p1);
; #pragma unroll
;         for (int nt = 0; nt < 8; ++nt) acc[nt] = mfma16(av, bfr[nt], acc[nt]);
;     }
.LBB0_582:
	s_andn2_b64 vcc, exec, s[2:3]
	s_cbranch_vccnz .LBB0_221
	s_bfe_u32 s14, s13, 0x20004
	v_mov_b32_e32 v55, v224
	s_mov_b64 s[2:3], s[0:1]
	s_lshl_b32 s40, s14, 21
	s_load_dwordx2 s[22:23], s[2:3], 0xd0
	s_cmp_gt_u32 s13, 63
	s_mov_b32 s2, 0x1f018000
	s_cselect_b32 s92, s2, 0x1e818000
	s_mov_b64 s[24:25], s[92:93]
	s_mov_b64 s[2:3], s[0:1]
	s_mov_b64 s[20:21], s[0:1]
	s_load_dwordx2 s[2:3], s[2:3], 0x48
	s_load_dwordx2 s[20:21], s[20:21], 0x40
	s_waitcnt lgkmcnt(0)
	s_cselect_b32 s41, s3, s21
	s_cselect_b32 s42, s2, s20
	s_mov_b64 s[2:3], s[0:1]
	s_load_dwordx2 s[26:27], s[2:3], 0xd0
	s_mov_b32 s2, 0xab08000
	s_cselect_b32 s92, s2, 0xaa08000
	s_mov_b32 s15, 0xac10000
	s_mov_b64 s[38:39], s[92:93]
	s_cselect_b32 s92, s15, 0xac08000
	s_lshl_b32 s15, s13, 4
	v_and_b32_e32 v54, 15, v55
	s_and_b32 s15, s15, 0xf0
	s_waitcnt vmcnt(3)
	v_or_b32_e32 v0, s15, v54
	s_movk_i32 s43, 0xff
	v_ashrrev_i32_e32 v56, 6, v55
	v_lshlrev_b32_e32 v1, 11, v0
	v_cmp_ne_u32_e32 vcc, s43, v0
	v_mov_b32_e32 v0, 0x7f000
	v_lshlrev_b32_e32 v214, 13, v54
	s_waitcnt vmcnt(0)
	v_cndmask_b32_e32 v4, v0, v1, vcc
	v_lshlrev_b32_e32 v0, 9, v56
	v_lshl_add_u64 v[2:3], s[38:39], 0, v[214:215]
	v_and_b32_e32 v214, 48, v55
	v_ashrrev_i32_e32 v1, 31, v0
	v_lshl_add_u64 v[2:3], v[2:3], 0, v[214:215]
	s_mov_b64 s[2:3], s[0:1]
	v_lshl_add_u64 v[2:3], v[0:1], 1, v[2:3]
	v_lshlrev_b64 v[34:35], 2, v[0:1]
	s_add_u32 s24, s24, s40
	v_lshlrev_b32_e32 v0, 1, v55
	s_addc_u32 s25, s25, 0
	v_and_b32_e32 v214, 0x60, v0
	s_load_dwordx2 s[2:3], s[2:3], 0xd0
	s_waitcnt lgkmcnt(0)
	v_lshl_add_u64 v[32:33], s[26:27], 0, v[2:3]
	v_lshl_add_u64 v[0:1], s[24:25], 0, v[214:215]
	v_lshlrev_b32_e32 v2, 2, v4
	v_mov_b32_e32 v3, v215
	v_lshl_add_u64 v[0:1], v[0:1], 0, v[2:3]
	v_lshl_add_u64 v[36:37], s[22:23], 0, v[0:1]
	s_add_u32 s22, s42, s16
	s_mov_b64 s[20:21], s[92:93]
	s_mov_b32 s43, 0
	s_mov_b32 s44, 0
	s_mov_b32 s45, 0
	s_mov_b32 s46, 0
	s_mov_b32 s47, 0
	s_mov_b32 s48, 0
	s_mov_b32 s49, 0
	s_mov_b32 s50, s93
	s_addc_u32 s23, s41, s17
	v_lshrrev_b32_e32 v57, 4, v55
	v_lshl_add_u64 v[38:39], s[22:23], 0, v[214:215]
	s_mov_b64 s[22:23], 0
	v_mov_b32_e32 v0, s43
	v_mov_b32_e32 v8, s44
	v_mov_b32_e32 v4, s45
	v_mov_b32_e32 v20, s46
	v_mov_b32_e32 v12, s47
	v_mov_b32_e32 v24, s48
	v_mov_b32_e32 v16, s49
	v_mov_b32_e32 v28, s50
	v_mov_b32_e32 v1, s43
	v_mov_b32_e32 v2, s43
	v_mov_b32_e32 v3, s43
	v_mov_b32_e32 v9, s44
	v_mov_b32_e32 v10, s44
	v_mov_b32_e32 v11, s44
	v_mov_b32_e32 v5, s45
	v_mov_b32_e32 v6, s45
	v_mov_b32_e32 v7, s45
	v_mov_b32_e32 v21, s46
	v_mov_b32_e32 v22, s46
	v_mov_b32_e32 v23, s46
	v_mov_b32_e32 v13, s47
	v_mov_b32_e32 v14, s47
	v_mov_b32_e32 v15, s47
	v_mov_b32_e32 v25, s48
	v_mov_b32_e32 v26, s48
	v_mov_b32_e32 v27, s48
	v_mov_b32_e32 v17, s49
	v_mov_b32_e32 v18, s49
	v_mov_b32_e32 v19, s49
	v_mov_b32_e32 v29, s50
	v_mov_b32_e32 v30, s50
	v_mov_b32_e32 v31, s50
	s_barrier
	v_lshl_add_u64 v[40:41], v[36:37], 0, v[34:35]
	v_lshl_add_u64 v[42:43], v[38:39], 0, v[34:35]
	global_load_dwordx4 v[128:131], v[40:41], off
	global_load_dwordx4 v[132:135], v[40:41], off offset:16
	global_load_dwordx4 v[136:139], v[42:43], off
	global_load_dwordx4 v[140:143], v[42:43], off offset:16
	global_load_dwordx4 v[144:147], v[40:41], off offset:128
	global_load_dwordx4 v[148:151], v[40:41], off offset:144
	global_load_dwordx4 v[152:155], v[42:43], off offset:128
	global_load_dwordx4 v[156:159], v[42:43], off offset:144
	global_load_dwordx4 v[160:163], v[40:41], off offset:256
	global_load_dwordx4 v[164:167], v[40:41], off offset:272
	global_load_dwordx4 v[168:171], v[42:43], off offset:256
	global_load_dwordx4 v[172:175], v[42:43], off offset:272
	global_load_dwordx4 v[176:179], v[40:41], off offset:384
	global_load_dwordx4 v[180:183], v[40:41], off offset:400
	global_load_dwordx4 v[184:187], v[42:43], off offset:384
	global_load_dwordx4 v[188:191], v[42:43], off offset:400
	global_load_dwordx4 v[192:195], v[40:41], off offset:512
	global_load_dwordx4 v[196:199], v[40:41], off offset:528
	global_load_dwordx4 v[200:203], v[42:43], off offset:512
	global_load_dwordx4 v[204:207], v[42:43], off offset:528
	global_load_dwordx4 v[208:211], v[40:41], off offset:640
	global_load_dwordx4 v[216:219], v[40:41], off offset:656
	global_load_dwordx4 v[220:223], v[42:43], off offset:640
	global_load_dwordx4 v[238:241], v[42:43], off offset:656
	v_add_co_u32_e32 v44, vcc, 0x20000, v32
	s_nop 1
	v_addc_co_u32_e32 v45, vcc, 0, v33, vcc
	v_add_co_u32_e32 v46, vcc, 0x40000, v32
	s_nop 1
	v_addc_co_u32_e32 v47, vcc, 0, v33, vcc
	v_add_co_u32_e32 v48, vcc, 0x60000, v32
	s_nop 1
	v_addc_co_u32_e32 v49, vcc, 0, v33, vcc
	v_add_co_u32_e32 v50, vcc, 0x80000, v32
	s_nop 1
	v_addc_co_u32_e32 v51, vcc, 0, v33, vcc
	v_add_co_u32_e32 v52, vcc, 0xa0000, v32
	s_nop 1
	v_addc_co_u32_e32 v53, vcc, 0, v33, vcc
	v_add_co_u32_e32 v58, vcc, 0xc0000, v32
	s_nop 1
	v_addc_co_u32_e32 v59, vcc, 0, v33, vcc
	v_add_co_u32_e32 v60, vcc, 0xe0000, v32
	s_nop 1
	v_addc_co_u32_e32 v61, vcc, 0, v33, vcc
	s_waitcnt vmcnt(0)
; __device__ __forceinline__ f32x4 mfma16(bf16x8 a, bf16x8 b, f32x4 c) { return __builtin_amdgcn_mfma_f32_16x16x32_bf16(a, b, c, 0, 0, 0); }
; __device__ __forceinline__ void compress_item(const Args& a, int l, int it, unsigned char* lds, unsigned* cmp_done) {
;     ...
;     for (int kk = 0; kk < 16; ++kk) {
;         const f32x4 x0 = *(const f32x4*)(arow + kk * 32), x1 = *(const f32x4*)(arow + kk * 32 + 4);
;         const f32x4 p0 = *(const f32x4*)(per + kk * 32), p1 = *(const f32x4*)(per + kk * 32 + 4);
;         bf16x8 bfr[8];
; #pragma unroll
;         for (int nt = 0; nt < 8; ++nt) bfr[nt] = *(const bf16x8*)(brow + (size_t)nt * 16 * 4096 + kk * 32);
;         const bf16x8 av = pack8(x0 + p0, x1 + p1);
; #pragma unroll
;         for (int nt = 0; nt < 8; ++nt) acc[nt] = mfma16(av, bfr[nt], acc[nt]);
;     }
	v_pk_add_f32 v[128:129], v[128:129], v[136:137]
	v_pk_add_f32 v[130:131], v[130:131], v[138:139]
	v_pk_add_f32 v[132:133], v[132:133], v[140:141]
	v_pk_add_f32 v[134:135], v[134:135], v[142:143]
	v_cvt_pk_bf16_f32 v64, v128, v129
	v_cvt_pk_bf16_f32 v65, v130, v131
	v_cvt_pk_bf16_f32 v66, v132, v133
	v_cvt_pk_bf16_f32 v67, v134, v135
	v_pk_add_f32 v[144:145], v[144:145], v[152:153]
	v_pk_add_f32 v[146:147], v[146:147], v[154:155]
	v_pk_add_f32 v[148:149], v[148:149], v[156:157]
	v_pk_add_f32 v[150:151], v[150:151], v[158:159]
	v_cvt_pk_bf16_f32 v68, v144, v145
	v_cvt_pk_bf16_f32 v69, v146, v147
	v_cvt_pk_bf16_f32 v70, v148, v149
	v_cvt_pk_bf16_f32 v71, v150, v151
	v_pk_add_f32 v[160:161], v[160:161], v[168:169]
	v_pk_add_f32 v[162:163], v[162:163], v[170:171]
	v_pk_add_f32 v[164:165], v[164:165], v[172:173]
	v_pk_add_f32 v[166:167], v[166:167], v[174:175]
	v_cvt_pk_bf16_f32 v72, v160, v161
	v_cvt_pk_bf16_f32 v73, v162, v163
	v_cvt_pk_bf16_f32 v74, v164, v165
	v_cvt_pk_bf16_f32 v75, v166, v167
	v_pk_add_f32 v[176:177], v[176:177], v[184:185]
	v_pk_add_f32 v[178:179], v[178:179], v[186:187]
	v_pk_add_f32 v[180:181], v[180:181], v[188:189]
	v_pk_add_f32 v[182:183], v[182:183], v[190:191]
	v_cvt_pk_bf16_f32 v76, v176, v177
	v_cvt_pk_bf16_f32 v77, v178, v179
	v_cvt_pk_bf16_f32 v78, v180, v181
	v_cvt_pk_bf16_f32 v79, v182, v183
	v_pk_add_f32 v[192:193], v[192:193], v[200:201]
	v_pk_add_f32 v[194:195], v[194:195], v[202:203]
	v_pk_add_f32 v[196:197], v[196:197], v[204:205]
	v_pk_add_f32 v[198:199], v[198:199], v[206:207]
	v_cvt_pk_bf16_f32 v80, v192, v193
	v_cvt_pk_bf16_f32 v81, v194, v195
	v_cvt_pk_bf16_f32 v82, v196, v197
	v_cvt_pk_bf16_f32 v83, v198, v199
	v_pk_add_f32 v[208:209], v[208:209], v[220:221]
	v_pk_add_f32 v[210:211], v[210:211], v[222:223]
	v_pk_add_f32 v[216:217], v[216:217], v[238:239]
	v_pk_add_f32 v[218:219], v[218:219], v[240:241]
	v_cvt_pk_bf16_f32 v84, v208, v209
	v_cvt_pk_bf16_f32 v85, v210, v211
	v_cvt_pk_bf16_f32 v86, v216, v217
	v_cvt_pk_bf16_f32 v87, v218, v219
	global_load_dwordx4 v[128:131], v[40:41], off offset:768
	global_load_dwordx4 v[132:135], v[40:41], off offset:784
	global_load_dwordx4 v[136:139], v[42:43], off offset:768
	global_load_dwordx4 v[140:143], v[42:43], off offset:784
	global_load_dwordx4 v[144:147], v[40:41], off offset:896
	global_load_dwordx4 v[148:151], v[40:41], off offset:912
	global_load_dwordx4 v[152:155], v[42:43], off offset:896
	global_load_dwordx4 v[156:159], v[42:43], off offset:912
	global_load_dwordx4 v[160:163], v[40:41], off offset:1024
	global_load_dwordx4 v[164:167], v[40:41], off offset:1040
	global_load_dwordx4 v[168:171], v[42:43], off offset:1024
	global_load_dwordx4 v[172:175], v[42:43], off offset:1040
	global_load_dwordx4 v[176:179], v[40:41], off offset:1152
	global_load_dwordx4 v[180:183], v[40:41], off offset:1168
	global_load_dwordx4 v[184:187], v[42:43], off offset:1152
	global_load_dwordx4 v[188:191], v[42:43], off offset:1168
	global_load_dwordx4 v[192:195], v[40:41], off offset:1280
	global_load_dwordx4 v[196:199], v[40:41], off offset:1296
	global_load_dwordx4 v[200:203], v[42:43], off offset:1280
	global_load_dwordx4 v[204:207], v[42:43], off offset:1296
	global_load_dwordx4 v[208:211], v[40:41], off offset:1408
	global_load_dwordx4 v[216:219], v[40:41], off offset:1424
	global_load_dwordx4 v[220:223], v[42:43], off offset:1408
	global_load_dwordx4 v[238:241], v[42:43], off offset:1424
	s_waitcnt vmcnt(0)
	v_pk_add_f32 v[128:129], v[128:129], v[136:137]
	v_pk_add_f32 v[130:131], v[130:131], v[138:139]
	v_pk_add_f32 v[132:133], v[132:133], v[140:141]
	v_pk_add_f32 v[134:135], v[134:135], v[142:143]
	v_cvt_pk_bf16_f32 v88, v128, v129
	v_cvt_pk_bf16_f32 v89, v130, v131
	v_cvt_pk_bf16_f32 v90, v132, v133
	v_cvt_pk_bf16_f32 v91, v134, v135
	v_pk_add_f32 v[144:145], v[144:145], v[152:153]
	v_pk_add_f32 v[146:147], v[146:147], v[154:155]
	v_pk_add_f32 v[148:149], v[148:149], v[156:157]
	v_pk_add_f32 v[150:151], v[150:151], v[158:159]
	v_cvt_pk_bf16_f32 v92, v144, v145
	v_cvt_pk_bf16_f32 v93, v146, v147
	v_cvt_pk_bf16_f32 v94, v148, v149
	v_cvt_pk_bf16_f32 v95, v150, v151
	v_pk_add_f32 v[160:161], v[160:161], v[168:169]
	v_pk_add_f32 v[162:163], v[162:163], v[170:171]
	v_pk_add_f32 v[164:165], v[164:165], v[172:173]
	v_pk_add_f32 v[166:167], v[166:167], v[174:175]
	v_cvt_pk_bf16_f32 v96, v160, v161
	v_cvt_pk_bf16_f32 v97, v162, v163
	v_cvt_pk_bf16_f32 v98, v164, v165
	v_cvt_pk_bf16_f32 v99, v166, v167
	v_pk_add_f32 v[176:177], v[176:177], v[184:185]
	v_pk_add_f32 v[178:179], v[178:179], v[186:187]
	v_pk_add_f32 v[180:181], v[180:181], v[188:189]
	v_pk_add_f32 v[182:183], v[182:183], v[190:191]
	v_cvt_pk_bf16_f32 v100, v176, v177
	v_cvt_pk_bf16_f32 v101, v178, v179
	v_cvt_pk_bf16_f32 v102, v180, v181
	v_cvt_pk_bf16_f32 v103, v182, v183
	v_pk_add_f32 v[192:193], v[192:193], v[200:201]
	v_pk_add_f32 v[194:195], v[194:195], v[202:203]
	v_pk_add_f32 v[196:197], v[196:197], v[204:205]
	v_pk_add_f32 v[198:199], v[198:199], v[206:207]
	v_cvt_pk_bf16_f32 v104, v192, v193
	v_cvt_pk_bf16_f32 v105, v194, v195
	v_cvt_pk_bf16_f32 v106, v196, v197
	v_cvt_pk_bf16_f32 v107, v198, v199
	v_pk_add_f32 v[208:209], v[208:209], v[220:221]
	v_pk_add_f32 v[210:211], v[210:211], v[222:223]
	v_pk_add_f32 v[216:217], v[216:217], v[238:239]
	v_pk_add_f32 v[218:219], v[218:219], v[240:241]
	v_cvt_pk_bf16_f32 v108, v208, v209
	v_cvt_pk_bf16_f32 v109, v210, v211
	v_cvt_pk_bf16_f32 v110, v216, v217
	v_cvt_pk_bf16_f32 v111, v218, v219
	global_load_dwordx4 v[128:131], v[40:41], off offset:1536
	global_load_dwordx4 v[132:135], v[40:41], off offset:1552
	global_load_dwordx4 v[136:139], v[42:43], off offset:1536
	global_load_dwordx4 v[140:143], v[42:43], off offset:1552
	global_load_dwordx4 v[144:147], v[40:41], off offset:1664
	global_load_dwordx4 v[148:151], v[40:41], off offset:1680
	global_load_dwordx4 v[152:155], v[42:43], off offset:1664
	global_load_dwordx4 v[156:159], v[42:43], off offset:1680
	global_load_dwordx4 v[160:163], v[40:41], off offset:1792
	global_load_dwordx4 v[164:167], v[40:41], off offset:1808
	global_load_dwordx4 v[168:171], v[42:43], off offset:1792
	global_load_dwordx4 v[172:175], v[42:43], off offset:1808
	global_load_dwordx4 v[176:179], v[40:41], off offset:1920
	global_load_dwordx4 v[180:183], v[40:41], off offset:1936
	global_load_dwordx4 v[184:187], v[42:43], off offset:1920
	global_load_dwordx4 v[188:191], v[42:43], off offset:1936
	global_load_dwordx4 v[192:195], v[32:33], off
	global_load_dwordx4 v[196:199], v[44:45], off
	global_load_dwordx4 v[200:203], v[46:47], off
	global_load_dwordx4 v[204:207], v[48:49], off
	global_load_dwordx4 v[208:211], v[50:51], off
	global_load_dwordx4 v[216:219], v[52:53], off
	global_load_dwordx4 v[220:223], v[58:59], off
	global_load_dwordx4 v[238:241], v[60:61], off
	s_waitcnt vmcnt(8)
; __device__ __forceinline__ f32x4 mfma16(bf16x8 a, bf16x8 b, f32x4 c) { return __builtin_amdgcn_mfma_f32_16x16x32_bf16(a, b, c, 0, 0, 0); }
; __device__ __forceinline__ void compress_item(const Args& a, int l, int it, unsigned char* lds, unsigned* cmp_done) {
;     ...
;     for (int kk = 0; kk < 16; ++kk) {
;         const f32x4 x0 = *(const f32x4*)(arow + kk * 32), x1 = *(const f32x4*)(arow + kk * 32 + 4);
;         const f32x4 p0 = *(const f32x4*)(per + kk * 32), p1 = *(const f32x4*)(per + kk * 32 + 4);
;         bf16x8 bfr[8];
; #pragma unroll
;         for (int nt = 0; nt < 8; ++nt) bfr[nt] = *(const bf16x8*)(brow + (size_t)nt * 16 * 4096 + kk * 32);
;         const bf16x8 av = pack8(x0 + p0, x1 + p1);
; #pragma unroll
;         for (int nt = 0; nt < 8; ++nt) acc[nt] = mfma16(av, bfr[nt], acc[nt]);
;     }
	v_pk_add_f32 v[128:129], v[128:129], v[136:137]
	v_pk_add_f32 v[130:131], v[130:131], v[138:139]
	v_pk_add_f32 v[132:133], v[132:133], v[140:141]
	v_pk_add_f32 v[134:135], v[134:135], v[142:143]
	v_cvt_pk_bf16_f32 v112, v128, v129
	v_cvt_pk_bf16_f32 v113, v130, v131
	v_cvt_pk_bf16_f32 v114, v132, v133
	v_cvt_pk_bf16_f32 v115, v134, v135
	v_pk_add_f32 v[144:145], v[144:145], v[152:153]
	v_pk_add_f32 v[146:147], v[146:147], v[154:155]
	v_pk_add_f32 v[148:149], v[148:149], v[156:157]
	v_pk_add_f32 v[150:151], v[150:151], v[158:159]
	v_cvt_pk_bf16_f32 v116, v144, v145
	v_cvt_pk_bf16_f32 v117, v146, v147
	v_cvt_pk_bf16_f32 v118, v148, v149
	v_cvt_pk_bf16_f32 v119, v150, v151
	v_pk_add_f32 v[160:161], v[160:161], v[168:169]
	v_pk_add_f32 v[162:163], v[162:163], v[170:171]
	v_pk_add_f32 v[164:165], v[164:165], v[172:173]
	v_pk_add_f32 v[166:167], v[166:167], v[174:175]
	v_cvt_pk_bf16_f32 v120, v160, v161
	v_cvt_pk_bf16_f32 v121, v162, v163
	v_cvt_pk_bf16_f32 v122, v164, v165
	v_cvt_pk_bf16_f32 v123, v166, v167
	v_pk_add_f32 v[176:177], v[176:177], v[184:185]
	v_pk_add_f32 v[178:179], v[178:179], v[186:187]
	v_pk_add_f32 v[180:181], v[180:181], v[188:189]
	v_pk_add_f32 v[182:183], v[182:183], v[190:191]
	v_cvt_pk_bf16_f32 v124, v176, v177
	v_cvt_pk_bf16_f32 v125, v178, v179
	v_cvt_pk_bf16_f32 v126, v180, v181
	v_cvt_pk_bf16_f32 v127, v182, v183
	global_load_dwordx4 v[128:131], v[32:33], off offset:64
	global_load_dwordx4 v[132:135], v[44:45], off offset:64
	global_load_dwordx4 v[136:139], v[46:47], off offset:64
	global_load_dwordx4 v[140:143], v[48:49], off offset:64
	global_load_dwordx4 v[144:147], v[50:51], off offset:64
	global_load_dwordx4 v[148:151], v[52:53], off offset:64
	global_load_dwordx4 v[152:155], v[58:59], off offset:64
	global_load_dwordx4 v[156:159], v[60:61], off offset:64
	global_load_dwordx4 v[160:163], v[32:33], off offset:128
	global_load_dwordx4 v[164:167], v[44:45], off offset:128
	global_load_dwordx4 v[168:171], v[46:47], off offset:128
	global_load_dwordx4 v[172:175], v[48:49], off offset:128
	global_load_dwordx4 v[176:179], v[50:51], off offset:128
	global_load_dwordx4 v[180:183], v[52:53], off offset:128
	global_load_dwordx4 v[184:187], v[58:59], off offset:128
	global_load_dwordx4 v[188:191], v[60:61], off offset:128
	s_waitcnt vmcnt(16)
	v_mfma_f32_16x16x32_bf16 v[0:3], v[64:67], v[192:195], v[0:3]
	v_mfma_f32_16x16x32_bf16 v[8:11], v[64:67], v[196:199], v[8:11]
	v_mfma_f32_16x16x32_bf16 v[4:7], v[64:67], v[200:203], v[4:7]
	v_mfma_f32_16x16x32_bf16 v[20:23], v[64:67], v[204:207], v[20:23]
	v_mfma_f32_16x16x32_bf16 v[12:15], v[64:67], v[208:211], v[12:15]
	v_mfma_f32_16x16x32_bf16 v[24:27], v[64:67], v[216:219], v[24:27]
	v_mfma_f32_16x16x32_bf16 v[16:19], v[64:67], v[220:223], v[16:19]
	v_mfma_f32_16x16x32_bf16 v[28:31], v[64:67], v[238:241], v[28:31]
	global_load_dwordx4 v[192:195], v[32:33], off offset:192
	global_load_dwordx4 v[196:199], v[44:45], off offset:192
	global_load_dwordx4 v[200:203], v[46:47], off offset:192
	global_load_dwordx4 v[204:207], v[48:49], off offset:192
	global_load_dwordx4 v[208:211], v[50:51], off offset:192
	global_load_dwordx4 v[216:219], v[52:53], off offset:192
	global_load_dwordx4 v[220:223], v[58:59], off offset:192
	global_load_dwordx4 v[238:241], v[60:61], off offset:192
	s_waitcnt vmcnt(16)
	v_mfma_f32_16x16x32_bf16 v[0:3], v[68:71], v[128:131], v[0:3]
	v_mfma_f32_16x16x32_bf16 v[8:11], v[68:71], v[132:135], v[8:11]
	v_mfma_f32_16x16x32_bf16 v[4:7], v[68:71], v[136:139], v[4:7]
	v_mfma_f32_16x16x32_bf16 v[20:23], v[68:71], v[140:143], v[20:23]
	v_mfma_f32_16x16x32_bf16 v[12:15], v[68:71], v[144:147], v[12:15]
	v_mfma_f32_16x16x32_bf16 v[24:27], v[68:71], v[148:151], v[24:27]
	v_mfma_f32_16x16x32_bf16 v[16:19], v[68:71], v[152:155], v[16:19]
	v_mfma_f32_16x16x32_bf16 v[28:31], v[68:71], v[156:159], v[28:31]
	global_load_dwordx4 v[128:131], v[32:33], off offset:256
	global_load_dwordx4 v[132:135], v[44:45], off offset:256
	global_load_dwordx4 v[136:139], v[46:47], off offset:256
	global_load_dwordx4 v[140:143], v[48:49], off offset:256
	global_load_dwordx4 v[144:147], v[50:51], off offset:256
	global_load_dwordx4 v[148:151], v[52:53], off offset:256
	global_load_dwordx4 v[152:155], v[58:59], off offset:256
	global_load_dwordx4 v[156:159], v[60:61], off offset:256
	s_waitcnt vmcnt(16)
	v_mfma_f32_16x16x32_bf16 v[0:3], v[72:75], v[160:163], v[0:3]
	v_mfma_f32_16x16x32_bf16 v[8:11], v[72:75], v[164:167], v[8:11]
	v_mfma_f32_16x16x32_bf16 v[4:7], v[72:75], v[168:171], v[4:7]
	v_mfma_f32_16x16x32_bf16 v[20:23], v[72:75], v[172:175], v[20:23]
	v_mfma_f32_16x16x32_bf16 v[12:15], v[72:75], v[176:179], v[12:15]
	v_mfma_f32_16x16x32_bf16 v[24:27], v[72:75], v[180:183], v[24:27]
	v_mfma_f32_16x16x32_bf16 v[16:19], v[72:75], v[184:187], v[16:19]
	v_mfma_f32_16x16x32_bf16 v[28:31], v[72:75], v[188:191], v[28:31]
	global_load_dwordx4 v[160:163], v[32:33], off offset:320
	global_load_dwordx4 v[164:167], v[44:45], off offset:320
	global_load_dwordx4 v[168:171], v[46:47], off offset:320
	global_load_dwordx4 v[172:175], v[48:49], off offset:320
	global_load_dwordx4 v[176:179], v[50:51], off offset:320
	global_load_dwordx4 v[180:183], v[52:53], off offset:320
	global_load_dwordx4 v[184:187], v[58:59], off offset:320
	global_load_dwordx4 v[188:191], v[60:61], off offset:320
	s_waitcnt vmcnt(16)
; __device__ __forceinline__ f32x4 mfma16(bf16x8 a, bf16x8 b, f32x4 c) { return __builtin_amdgcn_mfma_f32_16x16x32_bf16(a, b, c, 0, 0, 0); }
; __device__ __forceinline__ void compress_item(const Args& a, int l, int it, unsigned char* lds, unsigned* cmp_done) {
;     ...
;     for (int kk = 0; kk < 16; ++kk) {
;         const f32x4 x0 = *(const f32x4*)(arow + kk * 32), x1 = *(const f32x4*)(arow + kk * 32 + 4);
;         const f32x4 p0 = *(const f32x4*)(per + kk * 32), p1 = *(const f32x4*)(per + kk * 32 + 4);
;         bf16x8 bfr[8];
; #pragma unroll
;         for (int nt = 0; nt < 8; ++nt) bfr[nt] = *(const bf16x8*)(brow + (size_t)nt * 16 * 4096 + kk * 32);
;         const bf16x8 av = pack8(x0 + p0, x1 + p1);
; #pragma unroll
;         for (int nt = 0; nt < 8; ++nt) acc[nt] = mfma16(av, bfr[nt], acc[nt]);
;     }
	v_mfma_f32_16x16x32_bf16 v[0:3], v[76:79], v[192:195], v[0:3]
	v_mfma_f32_16x16x32_bf16 v[8:11], v[76:79], v[196:199], v[8:11]
	v_mfma_f32_16x16x32_bf16 v[4:7], v[76:79], v[200:203], v[4:7]
	v_mfma_f32_16x16x32_bf16 v[20:23], v[76:79], v[204:207], v[20:23]
	v_mfma_f32_16x16x32_bf16 v[12:15], v[76:79], v[208:211], v[12:15]
	v_mfma_f32_16x16x32_bf16 v[24:27], v[76:79], v[216:219], v[24:27]
	v_mfma_f32_16x16x32_bf16 v[16:19], v[76:79], v[220:223], v[16:19]
	v_mfma_f32_16x16x32_bf16 v[28:31], v[76:79], v[238:241], v[28:31]
	global_load_dwordx4 v[192:195], v[32:33], off offset:384
	global_load_dwordx4 v[196:199], v[44:45], off offset:384
	global_load_dwordx4 v[200:203], v[46:47], off offset:384
	global_load_dwordx4 v[204:207], v[48:49], off offset:384
	global_load_dwordx4 v[208:211], v[50:51], off offset:384
	global_load_dwordx4 v[216:219], v[52:53], off offset:384
	global_load_dwordx4 v[220:223], v[58:59], off offset:384
	global_load_dwordx4 v[238:241], v[60:61], off offset:384
	s_waitcnt vmcnt(16)
	v_mfma_f32_16x16x32_bf16 v[0:3], v[80:83], v[128:131], v[0:3]
	v_mfma_f32_16x16x32_bf16 v[8:11], v[80:83], v[132:135], v[8:11]
	v_mfma_f32_16x16x32_bf16 v[4:7], v[80:83], v[136:139], v[4:7]
	v_mfma_f32_16x16x32_bf16 v[20:23], v[80:83], v[140:143], v[20:23]
	v_mfma_f32_16x16x32_bf16 v[12:15], v[80:83], v[144:147], v[12:15]
	v_mfma_f32_16x16x32_bf16 v[24:27], v[80:83], v[148:151], v[24:27]
	v_mfma_f32_16x16x32_bf16 v[16:19], v[80:83], v[152:155], v[16:19]
	v_mfma_f32_16x16x32_bf16 v[28:31], v[80:83], v[156:159], v[28:31]
	global_load_dwordx4 v[128:131], v[32:33], off offset:448
	global_load_dwordx4 v[132:135], v[44:45], off offset:448
	global_load_dwordx4 v[136:139], v[46:47], off offset:448
	global_load_dwordx4 v[140:143], v[48:49], off offset:448
	global_load_dwordx4 v[144:147], v[50:51], off offset:448
	global_load_dwordx4 v[148:151], v[52:53], off offset:448
	global_load_dwordx4 v[152:155], v[58:59], off offset:448
	global_load_dwordx4 v[156:159], v[60:61], off offset:448
	s_waitcnt vmcnt(16)
	v_mfma_f32_16x16x32_bf16 v[0:3], v[84:87], v[160:163], v[0:3]
	v_mfma_f32_16x16x32_bf16 v[8:11], v[84:87], v[164:167], v[8:11]
	v_mfma_f32_16x16x32_bf16 v[4:7], v[84:87], v[168:171], v[4:7]
	v_mfma_f32_16x16x32_bf16 v[20:23], v[84:87], v[172:175], v[20:23]
	v_mfma_f32_16x16x32_bf16 v[12:15], v[84:87], v[176:179], v[12:15]
	v_mfma_f32_16x16x32_bf16 v[24:27], v[84:87], v[180:183], v[24:27]
	v_mfma_f32_16x16x32_bf16 v[16:19], v[84:87], v[184:187], v[16:19]
	v_mfma_f32_16x16x32_bf16 v[28:31], v[84:87], v[188:191], v[28:31]
	global_load_dwordx4 v[160:163], v[32:33], off offset:512
	global_load_dwordx4 v[164:167], v[44:45], off offset:512
	global_load_dwordx4 v[168:171], v[46:47], off offset:512
	global_load_dwordx4 v[172:175], v[48:49], off offset:512
	global_load_dwordx4 v[176:179], v[50:51], off offset:512
	global_load_dwordx4 v[180:183], v[52:53], off offset:512
	global_load_dwordx4 v[184:187], v[58:59], off offset:512
	global_load_dwordx4 v[188:191], v[60:61], off offset:512
	s_waitcnt vmcnt(16)
	v_mfma_f32_16x16x32_bf16 v[0:3], v[88:91], v[192:195], v[0:3]
	v_mfma_f32_16x16x32_bf16 v[8:11], v[88:91], v[196:199], v[8:11]
	v_mfma_f32_16x16x32_bf16 v[4:7], v[88:91], v[200:203], v[4:7]
	v_mfma_f32_16x16x32_bf16 v[20:23], v[88:91], v[204:207], v[20:23]
	v_mfma_f32_16x16x32_bf16 v[12:15], v[88:91], v[208:211], v[12:15]
	v_mfma_f32_16x16x32_bf16 v[24:27], v[88:91], v[216:219], v[24:27]
	v_mfma_f32_16x16x32_bf16 v[16:19], v[88:91], v[220:223], v[16:19]
	v_mfma_f32_16x16x32_bf16 v[28:31], v[88:91], v[238:241], v[28:31]
	global_load_dwordx4 v[192:195], v[32:33], off offset:576
	global_load_dwordx4 v[196:199], v[44:45], off offset:576
	global_load_dwordx4 v[200:203], v[46:47], off offset:576
	global_load_dwordx4 v[204:207], v[48:49], off offset:576
	global_load_dwordx4 v[208:211], v[50:51], off offset:576
	global_load_dwordx4 v[216:219], v[52:53], off offset:576
	global_load_dwordx4 v[220:223], v[58:59], off offset:576
	global_load_dwordx4 v[238:241], v[60:61], off offset:576
	s_waitcnt vmcnt(16)
	v_mfma_f32_16x16x32_bf16 v[0:3], v[92:95], v[128:131], v[0:3]
	v_mfma_f32_16x16x32_bf16 v[8:11], v[92:95], v[132:135], v[8:11]
	v_mfma_f32_16x16x32_bf16 v[4:7], v[92:95], v[136:139], v[4:7]
	v_mfma_f32_16x16x32_bf16 v[20:23], v[92:95], v[140:143], v[20:23]
	v_mfma_f32_16x16x32_bf16 v[12:15], v[92:95], v[144:147], v[12:15]
	v_mfma_f32_16x16x32_bf16 v[24:27], v[92:95], v[148:151], v[24:27]
	v_mfma_f32_16x16x32_bf16 v[16:19], v[92:95], v[152:155], v[16:19]
	v_mfma_f32_16x16x32_bf16 v[28:31], v[92:95], v[156:159], v[28:31]
	global_load_dwordx4 v[128:131], v[32:33], off offset:640
	global_load_dwordx4 v[132:135], v[44:45], off offset:640
	global_load_dwordx4 v[136:139], v[46:47], off offset:640
	global_load_dwordx4 v[140:143], v[48:49], off offset:640
	global_load_dwordx4 v[144:147], v[50:51], off offset:640
	global_load_dwordx4 v[148:151], v[52:53], off offset:640
	global_load_dwordx4 v[152:155], v[58:59], off offset:640
	global_load_dwordx4 v[156:159], v[60:61], off offset:640
	s_waitcnt vmcnt(16)
	v_mfma_f32_16x16x32_bf16 v[0:3], v[96:99], v[160:163], v[0:3]
	v_mfma_f32_16x16x32_bf16 v[8:11], v[96:99], v[164:167], v[8:11]
	v_mfma_f32_16x16x32_bf16 v[4:7], v[96:99], v[168:171], v[4:7]
	v_mfma_f32_16x16x32_bf16 v[20:23], v[96:99], v[172:175], v[20:23]
	v_mfma_f32_16x16x32_bf16 v[12:15], v[96:99], v[176:179], v[12:15]
	v_mfma_f32_16x16x32_bf16 v[24:27], v[96:99], v[180:183], v[24:27]
	v_mfma_f32_16x16x32_bf16 v[16:19], v[96:99], v[184:187], v[16:19]
	v_mfma_f32_16x16x32_bf16 v[28:31], v[96:99], v[188:191], v[28:31]
	global_load_dwordx4 v[160:163], v[32:33], off offset:704
	global_load_dwordx4 v[164:167], v[44:45], off offset:704
	global_load_dwordx4 v[168:171], v[46:47], off offset:704
	global_load_dwordx4 v[172:175], v[48:49], off offset:704
	global_load_dwordx4 v[176:179], v[50:51], off offset:704
	global_load_dwordx4 v[180:183], v[52:53], off offset:704
	global_load_dwordx4 v[184:187], v[58:59], off offset:704
	global_load_dwordx4 v[188:191], v[60:61], off offset:704
	s_waitcnt vmcnt(16)
; __device__ __forceinline__ f32x4 mfma16(bf16x8 a, bf16x8 b, f32x4 c) { return __builtin_amdgcn_mfma_f32_16x16x32_bf16(a, b, c, 0, 0, 0); }
; __device__ __forceinline__ void compress_item(const Args& a, int l, int it, unsigned char* lds, unsigned* cmp_done) {
;     ...
;     for (int kk = 0; kk < 16; ++kk) {
;         const f32x4 x0 = *(const f32x4*)(arow + kk * 32), x1 = *(const f32x4*)(arow + kk * 32 + 4);
;         const f32x4 p0 = *(const f32x4*)(per + kk * 32), p1 = *(const f32x4*)(per + kk * 32 + 4);
;         bf16x8 bfr[8];
; #pragma unroll
;         for (int nt = 0; nt < 8; ++nt) bfr[nt] = *(const bf16x8*)(brow + (size_t)nt * 16 * 4096 + kk * 32);
;         const bf16x8 av = pack8(x0 + p0, x1 + p1);
; #pragma unroll
;         for (int nt = 0; nt < 8; ++nt) acc[nt] = mfma16(av, bfr[nt], acc[nt]);
;     }
	v_mfma_f32_16x16x32_bf16 v[0:3], v[100:103], v[192:195], v[0:3]
	v_mfma_f32_16x16x32_bf16 v[8:11], v[100:103], v[196:199], v[8:11]
	v_mfma_f32_16x16x32_bf16 v[4:7], v[100:103], v[200:203], v[4:7]
	v_mfma_f32_16x16x32_bf16 v[20:23], v[100:103], v[204:207], v[20:23]
	v_mfma_f32_16x16x32_bf16 v[12:15], v[100:103], v[208:211], v[12:15]
	v_mfma_f32_16x16x32_bf16 v[24:27], v[100:103], v[216:219], v[24:27]
	v_mfma_f32_16x16x32_bf16 v[16:19], v[100:103], v[220:223], v[16:19]
	v_mfma_f32_16x16x32_bf16 v[28:31], v[100:103], v[238:241], v[28:31]
	global_load_dwordx4 v[192:195], v[32:33], off offset:768
	global_load_dwordx4 v[196:199], v[44:45], off offset:768
	global_load_dwordx4 v[200:203], v[46:47], off offset:768
	global_load_dwordx4 v[204:207], v[48:49], off offset:768
	global_load_dwordx4 v[208:211], v[50:51], off offset:768
	global_load_dwordx4 v[216:219], v[52:53], off offset:768
	global_load_dwordx4 v[220:223], v[58:59], off offset:768
	global_load_dwordx4 v[238:241], v[60:61], off offset:768
	s_waitcnt vmcnt(16)
	v_mfma_f32_16x16x32_bf16 v[0:3], v[104:107], v[128:131], v[0:3]
	v_mfma_f32_16x16x32_bf16 v[8:11], v[104:107], v[132:135], v[8:11]
	v_mfma_f32_16x16x32_bf16 v[4:7], v[104:107], v[136:139], v[4:7]
	v_mfma_f32_16x16x32_bf16 v[20:23], v[104:107], v[140:143], v[20:23]
	v_mfma_f32_16x16x32_bf16 v[12:15], v[104:107], v[144:147], v[12:15]
	v_mfma_f32_16x16x32_bf16 v[24:27], v[104:107], v[148:151], v[24:27]
	v_mfma_f32_16x16x32_bf16 v[16:19], v[104:107], v[152:155], v[16:19]
	v_mfma_f32_16x16x32_bf16 v[28:31], v[104:107], v[156:159], v[28:31]
	global_load_dwordx4 v[128:131], v[32:33], off offset:832
	global_load_dwordx4 v[132:135], v[44:45], off offset:832
	global_load_dwordx4 v[136:139], v[46:47], off offset:832
	global_load_dwordx4 v[140:143], v[48:49], off offset:832
	global_load_dwordx4 v[144:147], v[50:51], off offset:832
	global_load_dwordx4 v[148:151], v[52:53], off offset:832
	global_load_dwordx4 v[152:155], v[58:59], off offset:832
	global_load_dwordx4 v[156:159], v[60:61], off offset:832
	s_waitcnt vmcnt(16)
	v_mfma_f32_16x16x32_bf16 v[0:3], v[108:111], v[160:163], v[0:3]
	v_mfma_f32_16x16x32_bf16 v[8:11], v[108:111], v[164:167], v[8:11]
	v_mfma_f32_16x16x32_bf16 v[4:7], v[108:111], v[168:171], v[4:7]
	v_mfma_f32_16x16x32_bf16 v[20:23], v[108:111], v[172:175], v[20:23]
	v_mfma_f32_16x16x32_bf16 v[12:15], v[108:111], v[176:179], v[12:15]
	v_mfma_f32_16x16x32_bf16 v[24:27], v[108:111], v[180:183], v[24:27]
	v_mfma_f32_16x16x32_bf16 v[16:19], v[108:111], v[184:187], v[16:19]
	v_mfma_f32_16x16x32_bf16 v[28:31], v[108:111], v[188:191], v[28:31]
	global_load_dwordx4 v[160:163], v[32:33], off offset:896
	global_load_dwordx4 v[164:167], v[44:45], off offset:896
	global_load_dwordx4 v[168:171], v[46:47], off offset:896
	global_load_dwordx4 v[172:175], v[48:49], off offset:896
	global_load_dwordx4 v[176:179], v[50:51], off offset:896
	global_load_dwordx4 v[180:183], v[52:53], off offset:896
	global_load_dwordx4 v[184:187], v[58:59], off offset:896
	global_load_dwordx4 v[188:191], v[60:61], off offset:896
	s_waitcnt vmcnt(16)
	v_mfma_f32_16x16x32_bf16 v[0:3], v[112:115], v[192:195], v[0:3]
	v_mfma_f32_16x16x32_bf16 v[8:11], v[112:115], v[196:199], v[8:11]
	v_mfma_f32_16x16x32_bf16 v[4:7], v[112:115], v[200:203], v[4:7]
	v_mfma_f32_16x16x32_bf16 v[20:23], v[112:115], v[204:207], v[20:23]
	v_mfma_f32_16x16x32_bf16 v[12:15], v[112:115], v[208:211], v[12:15]
	v_mfma_f32_16x16x32_bf16 v[24:27], v[112:115], v[216:219], v[24:27]
	v_mfma_f32_16x16x32_bf16 v[16:19], v[112:115], v[220:223], v[16:19]
	v_mfma_f32_16x16x32_bf16 v[28:31], v[112:115], v[238:241], v[28:31]
	global_load_dwordx4 v[192:195], v[32:33], off offset:960
	global_load_dwordx4 v[196:199], v[44:45], off offset:960
	global_load_dwordx4 v[200:203], v[46:47], off offset:960
	global_load_dwordx4 v[204:207], v[48:49], off offset:960
	global_load_dwordx4 v[208:211], v[50:51], off offset:960
	global_load_dwordx4 v[216:219], v[52:53], off offset:960
	global_load_dwordx4 v[220:223], v[58:59], off offset:960
	global_load_dwordx4 v[238:241], v[60:61], off offset:960
	s_waitcnt vmcnt(16)
	v_mfma_f32_16x16x32_bf16 v[0:3], v[116:119], v[128:131], v[0:3]
	v_mfma_f32_16x16x32_bf16 v[8:11], v[116:119], v[132:135], v[8:11]
	v_mfma_f32_16x16x32_bf16 v[4:7], v[116:119], v[136:139], v[4:7]
	v_mfma_f32_16x16x32_bf16 v[20:23], v[116:119], v[140:143], v[20:23]
	v_mfma_f32_16x16x32_bf16 v[12:15], v[116:119], v[144:147], v[12:15]
	v_mfma_f32_16x16x32_bf16 v[24:27], v[116:119], v[148:151], v[24:27]
	v_mfma_f32_16x16x32_bf16 v[16:19], v[116:119], v[152:155], v[16:19]
	v_mfma_f32_16x16x32_bf16 v[28:31], v[116:119], v[156:159], v[28:31]
	s_waitcnt vmcnt(8)
	v_mfma_f32_16x16x32_bf16 v[0:3], v[120:123], v[160:163], v[0:3]
	v_mfma_f32_16x16x32_bf16 v[8:11], v[120:123], v[164:167], v[8:11]
	v_mfma_f32_16x16x32_bf16 v[4:7], v[120:123], v[168:171], v[4:7]
	v_mfma_f32_16x16x32_bf16 v[20:23], v[120:123], v[172:175], v[20:23]
	v_mfma_f32_16x16x32_bf16 v[12:15], v[120:123], v[176:179], v[12:15]
	v_mfma_f32_16x16x32_bf16 v[24:27], v[120:123], v[180:183], v[24:27]
	v_mfma_f32_16x16x32_bf16 v[16:19], v[120:123], v[184:187], v[16:19]
	v_mfma_f32_16x16x32_bf16 v[28:31], v[120:123], v[188:191], v[28:31]
	s_waitcnt vmcnt(0)
; __device__ __forceinline__ f32x4 mfma16(bf16x8 a, bf16x8 b, f32x4 c) { return __builtin_amdgcn_mfma_f32_16x16x32_bf16(a, b, c, 0, 0, 0); }
; __device__ __forceinline__ void compress_item(const Args& a, int l, int it, unsigned char* lds, unsigned* cmp_done) {
;     ...
;         for (int nt = 0; nt < 8; ++nt) acc[nt] = mfma16(av, bfr[nt], acc[nt]);
;     }
; #pragma unroll
;     for (int nt = 0; nt < 8; ++nt)
; #pragma unroll
;         for (int j = 0; j < 4; ++j) Part[(w * 16 + fq * 4 + j) * 132 + nt * 16 + fr] = acc[nt][j];
;     __syncthreads();
	v_mfma_f32_16x16x32_bf16 v[0:3], v[124:127], v[192:195], v[0:3]
	v_mfma_f32_16x16x32_bf16 v[8:11], v[124:127], v[196:199], v[8:11]
	v_mfma_f32_16x16x32_bf16 v[4:7], v[124:127], v[200:203], v[4:7]
	v_mfma_f32_16x16x32_bf16 v[20:23], v[124:127], v[204:207], v[20:23]
	v_mfma_f32_16x16x32_bf16 v[12:15], v[124:127], v[208:211], v[12:15]
	v_mfma_f32_16x16x32_bf16 v[24:27], v[124:127], v[216:219], v[24:27]
	v_mfma_f32_16x16x32_bf16 v[16:19], v[124:127], v[220:223], v[16:19]
	v_mfma_f32_16x16x32_bf16 v[28:31], v[124:127], v[238:241], v[28:31]
	v_and_b32_e32 v33, 3, v57
	v_lshlrev_b32_e32 v34, 4, v56
	v_lshlrev_b32_e32 v32, 2, v33
	v_or_b32_e32 v35, v32, v34
	s_movk_i32 s22, 0x210
	v_lshlrev_b32_e32 v36, 2, v54
	v_mul_lo_u32 v35, v35, s22
	v_add3_u32 v35, 0, v36, v35
	v_add_u32_e32 v36, 0x2000, v35
	ds_write2_b32 v36, v0, v8 offset1:16
	ds_write2_b32 v36, v1, v9 offset0:132 offset1:148
	v_add_u32_e32 v0, 0x2400, v35
	ds_write2_b32 v0, v2, v10 offset0:8 offset1:24
	ds_write2_b32 v0, v3, v11 offset0:140 offset1:156
	ds_write2_b32 v36, v4, v20 offset0:32 offset1:48
	ds_write2_b32 v36, v5, v21 offset0:164 offset1:180
	ds_write2_b32 v0, v6, v22 offset0:40 offset1:56
	ds_write2_b32 v0, v7, v23 offset0:172 offset1:188
	ds_write2_b32 v36, v12, v24 offset0:64 offset1:80
	ds_write2_b32 v36, v13, v25 offset0:196 offset1:212
	ds_write2_b32 v0, v14, v26 offset0:72 offset1:88
	ds_write2_b32 v0, v15, v27 offset0:204 offset1:220
	ds_write2_b32 v36, v16, v28 offset0:96 offset1:112
	ds_write2_b32 v36, v17, v29 offset0:228 offset1:244
	ds_write2_b32 v0, v18, v30 offset0:104 offset1:120
	ds_write2_b32 v0, v19, v31 offset0:236 offset1:252
	v_ashrrev_i32_e32 v10, 5, v55
	v_lshlrev_b32_e32 v0, 2, v55
	v_and_b32_e32 v11, 0x7c, v0
	v_mul_lo_u32 v4, v10, s22
	v_add_u32_e32 v12, 0, v4
	v_lshlrev_b32_e32 v5, 2, v11
	v_add_u32_e32 v0, v12, v5
	v_add3_u32 v13, 0, v5, v4
	s_waitcnt lgkmcnt(0)
	s_barrier
; __device__ __forceinline__ unsigned pk2(float lo, float hi) { f32x2_t v = {lo, hi}; bf16x2_t b = __builtin_convertvector(v, bf16x2_t); return __builtin_bit_cast(unsigned, b); }
; __device__ __forceinline__ f32x4 mfma16(bf16x8 a, bf16x8 b, f32x4 c) { return __builtin_amdgcn_mfma_f32_16x16x32_bf16(a, b, c, 0, 0, 0); }
; #define WSP(T, off) ((T*)(__attribute__((address_space(1))) T*)(launder_ws(AWS, (off))))
; __device__ __forceinline__ void compress_item(const Args& a, int l, int it, unsigned char* lds, unsigned* cmp_done) {
;     ...
;     {
;         const int row = tid >> 5, c4 = (tid & 31) * 4;
;         f32x4 sum = *(const f32x4*)(Part + row * 132 + c4);
; #pragma unroll
;         for (int ww = 1; ww < 8; ++ww) sum = sum + *(const f32x4*)(Part + (ww * 16 + row) * 132 + c4);
;         u32x2 o; o.x = pk2(gelu_tanh(sum.x), gelu_tanh(sum.y)); o.y = pk2(gelu_tanh(sum.z), gelu_tanh(sum.w));
;         *(u32x2*)(Hs + row * 136 + c4) = o;
;     }
;     __syncthreads();
;     f32x4 acc2 = zero4();
; #pragma unroll
;     for (int ks = 0; ks < 4; ++ks)
;         acc2 = mfma16(*(const bf16x8*)(Hs + fr * 136 + ks * 32 + fq * 8), *(const bf16x8*)(W2t + (size_t)(w * 16 + fr) * 128 + ks * 32 + fq * 8), acc2);
;     const int dcol = w * 16 + fr;
;     if (which == 0) {
; #pragma unroll
;         for (int j = 0; j < 4; ++j) { const int r = rg * 16 + fq * 4 + j; WSP(bf16_t, WS_KCB)[((size_t)bg * 256 + r) * 128 + dcol] = r < 255 ? f2bf(acc2[j]) : (bf16_t)0; }
;     } else {
;         const int r0 = rg * 16 + fq * 4;
;         u32x2 o; o.x = pk2(acc2[0], acc2[1]); o.y = pk2(acc2[2], (r0 + 3 < 255) ? acc2[3] : 0.f);
;         *(u32x2*)(WSP(bf16_t, WS_VCT) + ((size_t)bg * 128 + dcol) * 256 + r0) = o;
;     }
	ds_read_b128 v[0:3], v0 offset:8192
	ds_read_b128 v[4:7], v13 offset:16640
	s_add_u32 s2, s2, s20
	s_addc_u32 s3, s3, s21
	v_lshlrev_b32_e32 v214, 4, v33
	s_cmp_gt_u32 s13, 63
	s_waitcnt lgkmcnt(0)
	v_pk_add_f32 v[6:7], v[2:3], v[6:7]
	v_pk_add_f32 v[4:5], v[0:1], v[4:5]
	ds_read_b128 v[0:3], v13 offset:25088
	s_movk_i32 s13, 0xfc
	s_waitcnt lgkmcnt(0)
	v_pk_add_f32 v[6:7], v[6:7], v[2:3]
	v_pk_add_f32 v[4:5], v[4:5], v[0:1]
	ds_read_b128 v[0:3], v13 offset:33536
	s_waitcnt lgkmcnt(0)
	v_pk_add_f32 v[6:7], v[6:7], v[2:3]
	v_pk_add_f32 v[4:5], v[4:5], v[0:1]
	ds_read_b128 v[0:3], v13 offset:41984
	s_waitcnt lgkmcnt(0)
	v_pk_add_f32 v[6:7], v[6:7], v[2:3]
	v_pk_add_f32 v[4:5], v[4:5], v[0:1]
	ds_read_b128 v[0:3], v13 offset:50432
	s_waitcnt lgkmcnt(0)
	v_pk_add_f32 v[6:7], v[6:7], v[2:3]
	v_pk_add_f32 v[4:5], v[4:5], v[0:1]
	ds_read_b128 v[0:3], v13 offset:58880
	s_waitcnt lgkmcnt(0)
	v_pk_add_f32 v[8:9], v[4:5], v[0:1]
	v_add_u32_e32 v0, 0x10700, v13
	v_pk_add_f32 v[6:7], v[6:7], v[2:3]
	ds_read_b128 v[2:5], v0
	s_waitcnt lgkmcnt(0)
	v_pk_add_f32 v[2:3], v[8:9], v[2:3]
	v_pk_add_f32 v[0:1], v[6:7], v[4:5]
	v_mul_f32_e32 v4, 0x3d372713, v2
	v_mul_f32_e32 v5, 0x3d372713, v3
	v_mul_f32_e32 v4, v2, v4
	v_mul_f32_e32 v5, v3, v5
	v_fma_f32 v4, v2, v4, v2
	v_fma_f32 v5, v3, v5, v3
	v_mul_f32_e32 v4, 0x3f4c422a, v4
	v_mul_f32_e32 v5, 0x3f4c422a, v5
	v_add_f32_e32 v4, v4, v4
	v_add_f32_e32 v5, v5, v5
	v_mul_f32_e32 v4, 0x3fb8aa3b, v4
	v_mul_f32_e32 v5, 0x3fb8aa3b, v5
	v_exp_f32_e32 v4, v4
	v_exp_f32_e32 v5, v5
	v_pk_mul_f32 v[2:3], v[2:3], 0.5 op_sel_hi:[1,0]
	v_pk_add_f32 v[4:5], v[4:5], 1.0 op_sel_hi:[1,0]
	s_nop 0
	v_div_scale_f32 v6, s[20:21], v5, v5, 2.0
	v_rcp_f32_e32 v7, v6
	s_nop 0
	v_fma_f32 v8, -v6, v7, 1.0
	v_fmac_f32_e32 v7, v8, v7
	v_div_scale_f32 v8, vcc, 2.0, v5, 2.0
	v_mul_f32_e32 v9, v8, v7
	v_fma_f32 v13, -v6, v9, v8
	v_fmac_f32_e32 v9, v13, v7
	v_fma_f32 v6, -v6, v9, v8
	v_div_fmas_f32 v6, v6, v7, v9
	v_div_fixup_f32 v5, v6, v5, 2.0
	v_div_scale_f32 v6, s[20:21], v4, v4, 2.0
	v_rcp_f32_e32 v7, v6
	s_nop 0
	v_fma_f32 v8, -v6, v7, 1.0
	v_fmac_f32_e32 v7, v8, v7
	v_div_scale_f32 v8, vcc, 2.0, v4, 2.0
	v_mul_f32_e32 v9, v8, v7
	v_fma_f32 v13, -v6, v9, v8
	v_fmac_f32_e32 v9, v13, v7
	v_fma_f32 v6, -v6, v9, v8
	v_div_fmas_f32 v6, v6, v7, v9
	v_div_fixup_f32 v4, v6, v4, 2.0
	v_pk_add_f32 v[4:5], v[4:5], 1.0 op_sel_hi:[1,0] neg_lo:[1,0] neg_hi:[1,0]
	s_nop 0
	v_pk_add_f32 v[4:5], v[4:5], 1.0 op_sel_hi:[1,0]
	s_nop 0
	v_pk_mul_f32 v[2:3], v[2:3], v[4:5]
	s_nop 0
	v_cvt_pk_bf16_f32 v2, v2, v3
	v_mul_f32_e32 v3, 0x3d372713, v0
	v_mul_f32_e32 v3, v0, v3
	v_fma_f32 v3, v0, v3, v0
	v_mul_f32_e32 v3, 0x3f4c422a, v3
	v_add_f32_e32 v3, v3, v3
	v_mul_f32_e32 v3, 0x3fb8aa3b, v3
	v_exp_f32_e32 v4, v3
	v_mul_f32_e32 v3, 0x3d372713, v1
	v_mul_f32_e32 v3, v1, v3
	v_fma_f32 v3, v1, v3, v1
	v_mul_f32_e32 v3, 0x3f4c422a, v3
	v_add_f32_e32 v3, v3, v3
	v_mul_f32_e32 v3, 0x3fb8aa3b, v3
	v_exp_f32_e32 v5, v3
	v_pk_mul_f32 v[0:1], v[0:1], 0.5 op_sel_hi:[1,0]
	v_pk_add_f32 v[4:5], v[4:5], 1.0 op_sel_hi:[1,0]
	s_nop 0
	v_div_scale_f32 v3, s[20:21], v5, v5, 2.0
	v_rcp_f32_e32 v6, v3
	s_nop 0
	v_fma_f32 v7, -v3, v6, 1.0
	v_fmac_f32_e32 v6, v7, v6
	v_div_scale_f32 v7, vcc, 2.0, v5, 2.0
	v_mul_f32_e32 v8, v7, v6
	v_fma_f32 v9, -v3, v8, v7
	v_fmac_f32_e32 v8, v9, v6
	v_fma_f32 v3, -v3, v8, v7
	v_div_fmas_f32 v3, v3, v6, v8
	v_div_fixup_f32 v5, v3, v5, 2.0
	v_div_scale_f32 v3, s[20:21], v4, v4, 2.0
	v_rcp_f32_e32 v6, v3
	s_mov_b32 s20, s93
	v_fma_f32 v7, -v3, v6, 1.0
	v_fmac_f32_e32 v6, v7, v6
	v_div_scale_f32 v7, vcc, 2.0, v4, 2.0
	v_mul_f32_e32 v8, v7, v6
	v_fma_f32 v9, -v3, v8, v7
	v_fmac_f32_e32 v8, v9, v6
	v_fma_f32 v3, -v3, v8, v7
	v_div_fmas_f32 v3, v3, v6, v8
	v_div_fixup_f32 v4, v3, v4, 2.0
	v_pk_add_f32 v[4:5], v[4:5], 1.0 op_sel_hi:[1,0] neg_lo:[1,0] neg_hi:[1,0]
	s_nop 0
	v_pk_add_f32 v[4:5], v[4:5], 1.0 op_sel_hi:[1,0]
	s_nop 0
	v_pk_mul_f32 v[0:1], v[0:1], v[4:5]
	v_mul_u32_u24_e32 v4, 0x110, v54
	v_add3_u32 v16, 0, v4, v214
	v_or_b32_e32 v4, v34, v54
	v_ashrrev_i32_e32 v5, 31, v4
	v_cvt_pk_bf16_f32 v3, v0, v1
	v_lshlrev_b32_e32 v0, 8, v10
	v_lshlrev_b64 v[6:7], 8, v[4:5]
	v_sub_u32_e32 v0, v12, v0
	v_lshl_add_u64 v[6:7], s[2:3], 0, v[6:7]
	v_lshl_add_u32 v0, v11, 1, v0
	v_lshl_add_u64 v[14:15], v[6:7], 0, v[214:215]
	ds_write_b64 v0, v[2:3]
	s_waitcnt lgkmcnt(0)
	s_barrier
	global_load_dwordx4 v[64:67], v[14:15], off
	global_load_dwordx4 v[68:71], v[14:15], off offset:64
	global_load_dwordx4 v[72:75], v[14:15], off offset:128
	global_load_dwordx4 v[76:79], v[14:15], off offset:192
	ds_read_b128 v[80:83], v16
	ds_read_b128 v[84:87], v16 offset:64
	ds_read_b128 v[88:91], v16 offset:128
	ds_read_b128 v[92:95], v16 offset:192
	v_mov_b32_e32 v0, s20
	v_mov_b32_e32 v1, s20
	v_mov_b32_e32 v2, s20
	v_mov_b32_e32 v3, s20
	s_mov_b64 s[2:3], -1
	s_waitcnt vmcnt(3) lgkmcnt(3)
	v_mfma_f32_16x16x32_bf16 v[0:3], v[80:83], v[64:67], v[0:3]
	s_waitcnt vmcnt(2) lgkmcnt(2)
	v_mfma_f32_16x16x32_bf16 v[0:3], v[84:87], v[68:71], v[0:3]
	s_waitcnt vmcnt(1) lgkmcnt(1)
	v_mfma_f32_16x16x32_bf16 v[0:3], v[88:91], v[72:75], v[0:3]
	s_waitcnt vmcnt(0) lgkmcnt(0)
	v_mfma_f32_16x16x32_bf16 v[0:3], v[92:95], v[76:79], v[0:3]
	v_or_b32_e32 v6, s15, v32
	v_cmp_ne_u32_e32 vcc, s13, v6
	s_cbranch_scc0 .LBB0_587
	s_mov_b64 s[2:3], s[0:1]
	s_load_dwordx2 s[2:3], s[2:3], 0xd0
	s_mov_b64 s[20:21], 0x20858000
	v_lshlrev_b64 v[10:11], 9, v[4:5]
	s_nop 0
	v_cndmask_b32_e32 v7, 0, v3, vcc
	s_waitcnt lgkmcnt(0)
	s_add_u32 s2, s2, s20
	s_addc_u32 s3, s3, s21
	s_lshl_b32 s13, s14, 16
	s_add_u32 s2, s2, s13
	s_addc_u32 s3, s3, 0
	v_lshl_add_u64 v[10:11], s[2:3], 0, v[10:11]
	v_lshlrev_b32_e32 v214, 1, v6
	v_cvt_pk_bf16_f32 v8, v0, v1
	v_cvt_pk_bf16_f32 v9, v2, v7
	v_lshl_add_u64 v[10:11], v[10:11], 0, v[214:215]
	global_store_dwordx2 v[10:11], v[8:9], off
	s_mov_b64 s[2:3], 0
